# diff-attention row-max exchange between lane halves via v_permlane32_swap instead of ds_bpermute (removes an LDS round trip from the QK->max->exp chain)
# speedup vs baseline: 1.0034x; 1.0034x over previous
; #define LAS __attribute__((address_space(3)))
; template <bool DIFF> ...
;     ...
;                 c0 = sl2 * (float)(64 * kt - wrow); c1 = sl2 * (float)(64 * kt + 32 - wrow);
;                 if (64 * kt + 64 > wrow) {
;                     asm volatile("" ::: "memory");
;                     const int irel = wrow + l32 - 64 * kt - hi * 4;
; #pragma unroll
;                     for (int r = 0; r < 16; ++r) { const int cr = (r >> 2) * 8 + (r & 3); if (cr > irel) s0[r] = -INFINITY; if (cr + 32 > irel) s1[r] = -INFINITY; }
;                 }
;             }
;             LAS const unsigned char* va = vb + (hi * 4 + ((lane & 15) >> 2)) * VSTR + (DIFF ? 0 : c * 256) + (((lane >> 4) & 1) * 16 + 4 * (lane & 3)) * 2;
;             bf16x8 fa[4], fb[4];
;             const int vq = (lane & 15) >> 2, vp = lane & 3, vg1 = (lane >> 4) & 1;
;             const int vs0 = 256 * (hi * 4 + vq) + 16 * ((2 * vg1 + (vp >> 1)) ^ hi) + 8 * (vp & 1), vs1 = 256 * (hi * 4 + 8 + vq) + 16 * ((2 * vg1 + (vp >> 1)) ^ (hi + 2)) + 8 * (vp & 1);
;     ...
;             float mx0 = s0[0], mx1 = s1[0];
; #pragma unroll
;             for (int r = 1; r < 16; r += 2) { mx0 = fmaxf(fmaxf(mx0, s0[r]), s0[r + 1 < 16 ? r + 1 : r]); mx1 = fmaxf(fmaxf(mx1, s1[r]), s1[r + 1 < 16 ? r + 1 : r]); }
;             float mx = fmaxf(__builtin_fmaf(mx0, sc2, c0), __builtin_fmaf(mx1, sc2, c1));
;             mx = fmaxf(mx, __shfl_xor(mx, 32));
;             __builtin_amdgcn_sched_barrier(0);
;             ATT_LOADG(fa, 0); ATT_LOADG(fb, 1);
;             __builtin_amdgcn_sched_barrier(0);
;             if (__builtin_amdgcn_ballot_w64(mx > m_run) != 0ull) {
;                 const float mnew = fmaxf(m_run, mx), alpha = __builtin_amdgcn_exp2f(m_run - mnew); m_run = mnew; l_run *= alpha;
; #pragma unroll
;                 for (int i = 0; i < 4; ++i)
; #pragma unroll
;                     for (int r = 0; r < 16; ++r) o[i][r] *= alpha;
;             }
.LBB0_119:
	s_add_i32 s0, s24, s22
	s_add_i32 s1, s0, 64
	s_addk_i32 s0, 0x60
	v_cvt_f32_i32_e32 v130, s1
	v_cvt_f32_i32_e32 v131, s0
	s_nop 5
	v_max_f32_e32 v132, v82, v82
	v_mul_f32_e32 v212, v182, v130
	v_mul_f32_e32 v213, v182, v131
	v_max_f32_e32 v130, v99, v99
	v_max_f32_e32 v131, v98, v98
	v_max_f32_e32 v130, v131, v130
	v_max_f32_e32 v131, v83, v83
	v_max_f32_e32 v131, v132, v131
	v_max3_f32 v130, v130, v100, v101
	v_max3_f32 v131, v131, v84, v85
	v_max3_f32 v130, v130, v102, v103
	v_max3_f32 v131, v131, v86, v87
	v_max3_f32 v130, v130, v104, v105
	v_max3_f32 v131, v131, v88, v89
	v_max3_f32 v130, v130, v106, v107
	v_max3_f32 v131, v131, v90, v91
	v_max3_f32 v130, v130, v108, v109
	v_max3_f32 v131, v131, v92, v93
	v_max3_f32 v130, v130, v110, v111
	v_max3_f32 v131, v131, v94, v95
	v_max3_f32 v130, v130, v112, v113
	v_max3_f32 v131, v131, v96, v97
	v_fmamk_f32 v130, v130, 0x3e38aa3b, v212
	v_fmamk_f32 v131, v131, 0x3e38aa3b, v213
	v_max_f32_e32 v214, v130, v131
	v_mov_b32_e32 v215, v214
	v_mov_b32_e32 v216, v214
	v_add_u32_e32 v130, s23, v186
	v_add_u32_e32 v131, s23, v198
	v_add3_u32 v210, v130, v163, v197
	v_add3_u32 v211, v131, v163, v197
	v_add_u32_e32 v228, v210, v199
	v_add_u32_e32 v229, v211, v199
	v_add_u32_e32 v230, v210, v206
	v_add_u32_e32 v231, v211, v206
	v_add_u32_e32 v232, v210, v207
	v_add_u32_e32 v233, v211, v207
	v_add_u32_e32 v234, v210, v208
	v_add_u32_e32 v235, v211, v208
	ds_read_b64_tr_b16 v[130:131], v228 offset:16384
	ds_read_b64_tr_b16 v[132:133], v229 offset:18432
	ds_read_b64_tr_b16 v[134:135], v230 offset:16384
	ds_read_b64_tr_b16 v[136:137], v231 offset:18432
	ds_read_b64_tr_b16 v[138:139], v232 offset:16384
	ds_read_b64_tr_b16 v[140:141], v233 offset:18432
	ds_read_b64_tr_b16 v[142:143], v234 offset:16384
	ds_read_b64_tr_b16 v[144:145], v235 offset:18432
	ds_read_b64_tr_b16 v[146:147], v228 offset:20480
	ds_read_b64_tr_b16 v[148:149], v229 offset:22528
	ds_read_b64_tr_b16 v[150:151], v230 offset:20480
	ds_read_b64_tr_b16 v[152:153], v231 offset:22528
	ds_read_b64_tr_b16 v[154:155], v232 offset:20480
	ds_read_b64_tr_b16 v[156:157], v233 offset:22528
	ds_read_b64_tr_b16 v[158:159], v234 offset:20480
	ds_read_b64_tr_b16 v[160:161], v235 offset:22528
	v_permlane32_swap_b32_e32 v215, v216
	s_nop 1
	v_max_f32_e32 v214, v215, v216
	v_cmp_gt_f32_e32 vcc, v214, v209
	s_cbranch_vccz .LBB0_112
	v_max_f32_e32 v214, v214, v214
	v_max_f32_e32 v215, v209, v209
	v_max_f32_e32 v215, v215, v214
	v_sub_f32_e32 v209, v209, v215
	v_exp_f32_e32 v214, v209
	v_mov_b32_e32 v209, v215
	v_pk_mul_f32 v[64:65], v[64:65], v[214:215] op_sel_hi:[1,0]
	v_pk_mul_f32 v[62:63], v[62:63], v[214:215] op_sel_hi:[1,0]
	v_pk_mul_f32 v[60:61], v[60:61], v[214:215] op_sel_hi:[1,0]
	v_pk_mul_f32 v[58:59], v[58:59], v[214:215] op_sel_hi:[1,0]
	v_pk_mul_f32 v[56:57], v[56:57], v[214:215] op_sel_hi:[1,0]
	v_pk_mul_f32 v[54:55], v[54:55], v[214:215] op_sel_hi:[1,0]
	v_pk_mul_f32 v[52:53], v[52:53], v[214:215] op_sel_hi:[1,0]
	v_pk_mul_f32 v[50:51], v[50:51], v[214:215] op_sel_hi:[1,0]
	v_pk_mul_f32 v[48:49], v[48:49], v[214:215] op_sel_hi:[1,0]
	v_pk_mul_f32 v[46:47], v[46:47], v[214:215] op_sel_hi:[1,0]
	v_pk_mul_f32 v[44:45], v[44:45], v[214:215] op_sel_hi:[1,0]
	v_pk_mul_f32 v[42:43], v[42:43], v[214:215] op_sel_hi:[1,0]
	v_pk_mul_f32 v[40:41], v[40:41], v[214:215] op_sel_hi:[1,0]
	v_pk_mul_f32 v[38:39], v[38:39], v[214:215] op_sel_hi:[1,0]
	v_pk_mul_f32 v[36:37], v[36:37], v[214:215] op_sel_hi:[1,0]
	v_pk_mul_f32 v[34:35], v[34:35], v[214:215] op_sel_hi:[1,0]
	v_pk_mul_f32 v[32:33], v[32:33], v[214:215] op_sel_hi:[1,0]
	v_pk_mul_f32 v[30:31], v[30:31], v[214:215] op_sel_hi:[1,0]
	v_pk_mul_f32 v[28:29], v[28:29], v[214:215] op_sel_hi:[1,0]
	v_pk_mul_f32 v[26:27], v[26:27], v[214:215] op_sel_hi:[1,0]
	v_pk_mul_f32 v[24:25], v[24:25], v[214:215] op_sel_hi:[1,0]
	v_pk_mul_f32 v[22:23], v[22:23], v[214:215] op_sel_hi:[1,0]
	v_pk_mul_f32 v[20:21], v[20:21], v[214:215] op_sel_hi:[1,0]
	v_pk_mul_f32 v[18:19], v[18:19], v[214:215] op_sel_hi:[1,0]
	v_pk_mul_f32 v[16:17], v[16:17], v[214:215] op_sel_hi:[1,0]
	v_pk_mul_f32 v[14:15], v[14:15], v[214:215] op_sel_hi:[1,0]
	v_pk_mul_f32 v[12:13], v[12:13], v[214:215] op_sel_hi:[1,0]
	v_pk_mul_f32 v[10:11], v[10:11], v[214:215] op_sel_hi:[1,0]
	v_pk_mul_f32 v[8:9], v[8:9], v[214:215] op_sel_hi:[1,0]
	v_pk_mul_f32 v[6:7], v[6:7], v[214:215] op_sel_hi:[1,0]
	v_pk_mul_f32 v[4:5], v[4:5], v[214:215] op_sel_hi:[1,0]
	v_pk_mul_f32 v[2:3], v[2:3], v[214:215] op_sel_hi:[1,0]
	v_mul_f32_e32 v205, v205, v214
	s_branch .LBB0_112
